# attn_item: half-tile stagger of waves 4-7 via mid-tile barrier, LDS staging write moved before mid barrier
# speedup vs baseline: 1.0004x; 1.0004x over previous
; __device__ __forceinline__ float bflo(unsigned u) { return __uint_as_float(u << 16); }
; __device__ __forceinline__ float bfhi(unsigned u) { return __uint_as_float(u & 0xffff0000u); }
; __device__ __forceinline__ void rope_cs(int pos, int i, float& c, float& s) {
;     const double rev = (double)pos * INVF[i] * 0.15915494309189535;
;     const float fr = (float)(rev - floor(rev));
;     c = __builtin_amdgcn_cosf(fr); s = __builtin_amdgcn_sinf(fr);
; __device__ __forceinline__ void q_prologue(const Params& p, int l, int qrow, int pos, int h, int hf, int lane, bf16x8 (&qf)[6]) {
;     ...
;     const bf16_t* qp = qraw + (size_t)qrow * 768 + h * DQK + 8 * hf;
;     float v[6][8];
; #pragma unroll
;     for (int s = 0; s < 6; ++s) { const u32x4 raw = *(const u32x4*)(qp + 16 * s);
;         v[s][0] = bflo(raw.x); v[s][1] = bfhi(raw.x); v[s][2] = bflo(raw.y); v[s][3] = bfhi(raw.y); v[s][4] = bflo(raw.z); v[s][5] = bfhi(raw.z); v[s][6] = bflo(raw.w); v[s][7] = bfhi(raw.w); }
; #pragma unroll
;     for (int e = 0; e < 8; ++e) { float c, s; rope_cs(pos, 8 * hf + e, c, s); const float x1 = v[4][e], x2 = v[5][e]; v[4][e] = x1 * c - x2 * s; v[5][e] = x1 * s + x2 * c; }
.LBB0_610:
	s_or_b64 exec, exec, s[48:49]
	s_bitcmp0_b32 s9, 0
	s_cselect_b32 s5, s16, s17
	s_ashr_i32 s10, s10, 6
	s_lshl_b32 s11, s5, 3
	s_movk_i32 s12, 0xd0
	v_and_b32_e32 v52, 63, v136
	v_and_b32_e32 v59, 31, v136
	v_bfe_u32 v246, v136, 5, 1
	s_add_i32 s10, s11, s10
	v_mad_u64_u32 v[234:235], s[12:13], v56, s12, v[0:1]
	v_mul_u32_u24_e32 v139, 0xd0, v138
	s_lshl_b32 s11, s10, 5
	v_add_u32_e32 v2, 16, v59
	s_add_i32 s12, s11, s20
	v_add_u32_e32 v232, s12, v2
	v_add_u32_e32 v26, s11, v2
	v_mov_b64_e32 v[2:3], s[24:25]
	s_movk_i32 s11, 0x600
	v_mad_i64_i32 v[2:3], s[12:13], v232, s11, v[2:3]
	v_lshlrev_b32_e32 v236, 4, v246
	v_mov_b32_e32 v237, v1
	v_lshl_add_u64 v[18:19], v[2:3], 0, v[236:237]
	v_lshlrev_b32_e32 v36, 6, v246
	s_getpc_b64 s[12:13]
	s_add_u32 s12, s12, _ZL4INVF@rel32@lo+4
	s_addc_u32 s13, s13, _ZL4INVF@rel32@hi+12
	global_load_dwordx4 v[2:5], v[18:19], off
	global_load_dwordx4 v[6:9], v[18:19], off offset:32
	global_load_dwordx4 v[10:13], v[18:19], off offset:64
	global_load_dwordx4 v[14:17], v[18:19], off offset:96
	global_load_dwordx4 v[22:25], v[18:19], off offset:128
	s_nop 0
	global_load_dwordx4 v[18:21], v[18:19], off offset:160
	v_cvt_f64_i32_e32 v[34:35], v26
	global_load_dwordx4 v[26:29], v36, s[12:13] offset:48
	global_load_dwordx4 v[30:33], v36, s[12:13] offset:32
	global_load_dwordx4 v[42:45], v36, s[12:13] offset:16
	global_load_dwordx4 v[38:41], v36, s[12:13]
	v_and_b32_e32 v126, 32, v136
	s_movk_i32 s11, 0x90
	v_mad_u64_u32 v[238:239], s[12:13], v56, s11, v[0:1]
	v_add_u32_e32 v0, 0, v238
	s_waitcnt vmcnt(9)
	v_lshlrev_b32_e32 v128, 16, v2
	s_waitcnt vmcnt(8)
	v_lshlrev_b32_e32 v92, 16, v9
	s_waitcnt vmcnt(7)
	v_lshlrev_b32_e32 v84, 16, v13
	s_waitcnt vmcnt(6)
	v_lshlrev_b32_e32 v82, 16, v14
	s_waitcnt vmcnt(3)
	v_mul_f64 v[26:27], v[26:27], v[34:35]
	s_waitcnt vmcnt(2)
	v_mul_f64 v[30:31], v[30:31], v[34:35]
	s_waitcnt vmcnt(1)
	v_mul_f64 v[44:45], v[44:45], v[34:35]
	s_waitcnt vmcnt(0)
	v_mul_f64 v[40:41], v[40:41], v[34:35]
	v_mul_f64 v[36:37], v[38:39], v[34:35]
	v_mul_f64 v[46:47], v[40:41], s[22:23]
	v_mul_f64 v[38:39], v[36:37], s[22:23]
	v_floor_f64_e32 v[46:47], v[46:47]
	v_floor_f64_e32 v[38:39], v[38:39]
	v_fma_f64 v[40:41], v[40:41], s[22:23], -v[46:47]
	v_fma_f64 v[36:37], v[36:37], s[22:23], -v[38:39]
	v_cvt_f32_f64_e32 v39, v[40:41]
	v_mul_f64 v[40:41], v[42:43], v[34:35]
	v_mul_f64 v[46:47], v[44:45], s[22:23]
	v_mul_f64 v[42:43], v[40:41], s[22:23]
	v_floor_f64_e32 v[46:47], v[46:47]
	v_floor_f64_e32 v[42:43], v[42:43]
	v_fma_f64 v[44:45], v[44:45], s[22:23], -v[46:47]
	v_fma_f64 v[40:41], v[40:41], s[22:23], -v[42:43]
	v_cvt_f32_f64_e32 v43, v[44:45]
	v_mul_f64 v[44:45], v[30:31], s[22:23]
	v_floor_f64_e32 v[44:45], v[44:45]
	v_fma_f64 v[30:31], v[30:31], s[22:23], -v[44:45]
	v_cvt_f32_f64_e32 v30, v[30:31]
	v_cos_f32_e32 v44, v30
	v_sin_f32_e32 v46, v30
	v_mul_f64 v[30:31], v[32:33], v[34:35]
	v_mul_f64 v[32:33], v[30:31], s[22:23]
	v_floor_f64_e32 v[32:33], v[32:33]
	v_fma_f64 v[30:31], v[30:31], s[22:23], -v[32:33]
	v_cvt_f32_f64_e32 v30, v[30:31]
	v_cos_f32_e32 v45, v30
	v_sin_f32_e32 v47, v30
	v_mul_f64 v[30:31], v[26:27], s[22:23]
	v_floor_f64_e32 v[30:31], v[30:31]
	v_fma_f64 v[26:27], v[26:27], s[22:23], -v[30:31]
	v_cvt_f32_f64_e32 v26, v[26:27]
	v_cos_f32_e32 v48, v26
	v_sin_f32_e32 v50, v26
	v_mul_f64 v[26:27], v[28:29], v[34:35]
	v_mul_f64 v[28:29], v[26:27], s[22:23]
	v_floor_f64_e32 v[28:29], v[28:29]
	v_fma_f64 v[26:27], v[26:27], s[22:23], -v[28:29]
	v_cvt_f32_f64_e32 v37, v[36:37]
	v_cvt_f32_f64_e32 v41, v[40:41]
	v_cvt_f32_f64_e32 v26, v[26:27]
	v_cos_f32_e32 v36, v37
	v_sin_f32_e32 v38, v37
	v_cos_f32_e32 v37, v39
	v_cos_f32_e32 v40, v41
	v_sin_f32_e32 v42, v41
	v_cos_f32_e32 v41, v43
	v_cos_f32_e32 v49, v26
	v_sin_f32_e32 v39, v39
	v_sin_f32_e32 v43, v43
	v_sin_f32_e32 v51, v26
	v_lshlrev_b32_e32 v72, 16, v20
	v_and_b32_e32 v73, 0xffff0000, v20
	v_lshlrev_b32_e32 v26, 2, v52
	v_lshlrev_b32_e32 v54, 16, v21
	v_and_b32_e32 v55, 0xffff0000, v21
	v_lshlrev_b32_e32 v70, 16, v24
	v_and_b32_e32 v71, 0xffff0000, v24
	v_pk_mul_f32 v[20:21], v[44:45], v[72:73]
	v_lshlrev_b32_e32 v76, 16, v19
	v_and_b32_e32 v77, 0xffff0000, v19
	v_lshlrev_b32_e32 v80, 16, v18
	v_and_b32_e32 v81, 0xffff0000, v18
	v_xor_b32_e32 v235, 0x80, v26
	v_lshlrev_b32_e32 v52, 16, v25
	v_and_b32_e32 v53, 0xffff0000, v25
	v_pk_mul_f32 v[26:27], v[48:49], v[54:55]
	v_pk_fma_f32 v[62:63], v[46:47], v[70:71], v[20:21]
	v_lshlrev_b32_e32 v74, 16, v23
	v_and_b32_e32 v75, 0xffff0000, v23
	v_pk_mul_f32 v[20:21], v[40:41], v[76:77]
	v_lshlrev_b32_e32 v78, 16, v22
	v_and_b32_e32 v79, 0xffff0000, v22
	v_pk_mul_f32 v[18:19], v[36:37], v[80:81]
	v_pk_fma_f32 v[60:61], v[50:51], v[52:53], v[26:27]
	v_pk_fma_f32 v[64:65], v[42:43], v[74:75], v[20:21]
	v_pk_fma_f32 v[22:23], v[38:39], v[78:79], v[18:19]
	v_pk_mul_f32 v[50:51], v[50:51], v[54:55]
	v_pk_mul_f32 v[46:47], v[46:47], v[72:73]
	v_pk_mul_f32 v[42:43], v[42:43], v[76:77]
	v_pk_mul_f32 v[38:39], v[38:39], v[80:81]
	global_load_dwordx4 v[24:27], v126, s[30:31] offset:336
	global_load_dwordx4 v[28:31], v126, s[30:31] offset:320
	global_load_dwordx4 v[18:21], v126, s[30:31] offset:272
	global_load_dwordx4 v[32:35], v126, s[30:31] offset:256
	v_pk_fma_f32 v[68:69], v[48:49], v[52:53], v[50:51] neg_lo:[0,0,1] neg_hi:[0,0,1]
	v_pk_fma_f32 v[70:71], v[44:45], v[70:71], v[46:47] neg_lo:[0,0,1] neg_hi:[0,0,1]
	v_pk_fma_f32 v[72:73], v[40:41], v[74:75], v[42:43] neg_lo:[0,0,1] neg_hi:[0,0,1]
	v_pk_fma_f32 v[74:75], v[36:37], v[78:79], v[38:39] neg_lo:[0,0,1] neg_hi:[0,0,1]
	v_lshlrev_b32_e32 v76, 16, v17
	v_and_b32_e32 v77, 0xffff0000, v17
	global_load_dwordx4 v[36:39], v126, s[30:31] offset:208
; #define LAS __attribute__((address_space(3)))
; __device__ __forceinline__ float shx32(float v, int lane) { return __int_as_float(__builtin_amdgcn_ds_bpermute((lane ^ 32) << 2, __float_as_int(v))); }
; __device__ __forceinline__ void q_prologue(const Params& p, int l, int qrow, int pos, int h, int hf, int lane, bf16x8 (&qf)[6]) {
;     ...
;     float ss = 0.f;
; #pragma unroll
;     for (int s = 0; s < 6; ++s)
; #pragma unroll
;         for (int e = 0; e < 8; ++e) ss += v[s][e] * v[s][e];
;     ss += shx32(ss, lane);
; __device__ __forceinline__ void attn_item(const Params& p, int l, LAS unsigned char* lds, int b, int h, int J) {
;     ...
;     u32x4 skn = *(const u32x4*)gkn, svt = *(const u32x4*)gvt, skr = {0u, 0u, 0u, 0u};
;     if (has_kr) skr = *(const u32x4*)gkr;
;     __builtin_amdgcn_sched_barrier(0);
;     bf16x8 qf[6];
;     q_prologue(p, l, qrow0 + r, NMETA + 32 * i + r, h, hf, lane, qf);
;     *(LAS u32x4*)(lds + wkn) = skn; *(LAS u32x4*)(lds + wvt) = svt; if (has_kr) *(LAS u32x4*)(lds + wkr) = skr;
;     __syncthreads();
	global_load_dwordx4 v[40:43], v126, s[30:31] offset:192
	v_lshlrev_b32_e32 v78, 16, v16
	v_and_b32_e32 v79, 0xffff0000, v16
	v_lshlrev_b32_e32 v80, 16, v15
	v_and_b32_e32 v81, 0xffff0000, v15
	v_and_b32_e32 v83, 0xffff0000, v14
	v_and_b32_e32 v85, 0xffff0000, v13
	global_load_dwordx4 v[14:17], v126, s[30:31] offset:144
	global_load_dwordx4 v[44:47], v126, s[30:31] offset:128
	v_lshlrev_b32_e32 v86, 16, v12
	v_and_b32_e32 v87, 0xffff0000, v12
	v_lshlrev_b32_e32 v88, 16, v11
	v_and_b32_e32 v89, 0xffff0000, v11
	v_lshlrev_b32_e32 v90, 16, v10
	v_and_b32_e32 v91, 0xffff0000, v10
	v_and_b32_e32 v93, 0xffff0000, v9
	global_load_dwordx4 v[10:13], v126, s[30:31] offset:80
	global_load_dwordx4 v[48:51], v126, s[30:31] offset:64
	v_lshlrev_b32_e32 v96, 16, v8
	v_and_b32_e32 v97, 0xffff0000, v8
	v_lshlrev_b32_e32 v116, 16, v7
	v_and_b32_e32 v117, 0xffff0000, v7
	v_lshlrev_b32_e32 v114, 16, v6
	v_and_b32_e32 v115, 0xffff0000, v6
	global_load_dwordx4 v[6:9], v126, s[30:31] offset:16
	global_load_dwordx4 v[52:55], v126, s[30:31]
	v_and_b32_e32 v129, 0xffff0000, v2
	v_lshlrev_b32_e32 v118, 16, v5
	v_and_b32_e32 v119, 0xffff0000, v5
	v_lshlrev_b32_e32 v126, 16, v4
	v_and_b32_e32 v127, 0xffff0000, v4
	v_lshlrev_b32_e32 v4, 16, v3
	v_and_b32_e32 v5, 0xffff0000, v3
	v_pk_mul_f32 v[2:3], v[128:129], v[128:129]
	v_pk_mul_f32 v[166:167], v[4:5], v[4:5]
	v_add_f32_e32 v2, v2, v3
	v_add_f32_e32 v2, v166, v2
	v_pk_mul_f32 v[164:165], v[126:127], v[126:127]
	v_add_f32_e32 v2, v167, v2
	v_add_f32_e32 v2, v164, v2
	v_pk_mul_f32 v[162:163], v[118:119], v[118:119]
	v_add_f32_e32 v2, v165, v2
	v_add_f32_e32 v2, v162, v2
	v_pk_mul_f32 v[160:161], v[114:115], v[114:115]
	v_add_f32_e32 v2, v163, v2
	v_add_f32_e32 v2, v160, v2
	v_pk_mul_f32 v[158:159], v[116:117], v[116:117]
	v_add_f32_e32 v2, v161, v2
	v_add_f32_e32 v2, v158, v2
	v_pk_mul_f32 v[156:157], v[96:97], v[96:97]
	v_add_f32_e32 v2, v159, v2
	v_add_f32_e32 v2, v156, v2
	v_pk_mul_f32 v[154:155], v[92:93], v[92:93]
	v_add_f32_e32 v2, v157, v2
	v_add_f32_e32 v2, v154, v2
	v_pk_mul_f32 v[152:153], v[90:91], v[90:91]
	v_add_f32_e32 v2, v155, v2
	v_add_f32_e32 v2, v152, v2
	v_pk_mul_f32 v[150:151], v[88:89], v[88:89]
	v_add_f32_e32 v2, v153, v2
	v_add_f32_e32 v2, v150, v2
	v_pk_mul_f32 v[148:149], v[86:87], v[86:87]
	v_add_f32_e32 v2, v151, v2
	v_add_f32_e32 v2, v148, v2
	v_pk_mul_f32 v[146:147], v[84:85], v[84:85]
	v_add_f32_e32 v2, v149, v2
	v_add_f32_e32 v2, v146, v2
	v_pk_mul_f32 v[144:145], v[82:83], v[82:83]
	v_add_f32_e32 v2, v147, v2
	v_add_f32_e32 v2, v144, v2
	v_pk_mul_f32 v[142:143], v[80:81], v[80:81]
	v_add_f32_e32 v2, v145, v2
	v_add_f32_e32 v2, v142, v2
	v_pk_mul_f32 v[140:141], v[78:79], v[78:79]
	v_add_f32_e32 v2, v143, v2
	v_add_f32_e32 v2, v140, v2
	v_pk_mul_f32 v[132:133], v[76:77], v[76:77]
	v_add_f32_e32 v2, v141, v2
	v_add_f32_e32 v2, v132, v2
	v_pk_mul_f32 v[130:131], v[74:75], v[74:75]
	v_add_f32_e32 v2, v133, v2
	v_add_f32_e32 v2, v130, v2
	v_pk_mul_f32 v[124:125], v[72:73], v[72:73]
	v_add_f32_e32 v2, v131, v2
	v_add_f32_e32 v2, v124, v2
	v_pk_mul_f32 v[122:123], v[70:71], v[70:71]
	v_add_f32_e32 v2, v125, v2
	v_add_f32_e32 v2, v122, v2
	v_pk_mul_f32 v[120:121], v[68:69], v[68:69]
	v_add_f32_e32 v2, v123, v2
	v_add_f32_e32 v2, v120, v2
	v_pk_mul_f32 v[112:113], v[22:23], v[22:23]
	v_add_f32_e32 v2, v121, v2
	v_add_f32_e32 v2, v112, v2
	v_pk_mul_f32 v[110:111], v[64:65], v[64:65]
	v_add_f32_e32 v2, v113, v2
	v_add_f32_e32 v2, v110, v2
	v_pk_mul_f32 v[94:95], v[62:63], v[62:63]
	v_add_f32_e32 v2, v111, v2
	v_add_f32_e32 v2, v94, v2
	v_pk_mul_f32 v[66:67], v[60:61], v[60:61]
	v_add_f32_e32 v2, v95, v2
	v_add_f32_e32 v2, v66, v2
	v_add_f32_e32 v2, v67, v2
	ds_bpermute_b32 v3, v235, v2
	v_add_u32_e32 v66, 0, v234
	ds_write_b128 v66, v[98:101]
	ds_write_b128 v0, v[102:105] offset:13312
	s_and_saveexec_b64 s[48:49], s[40:41]
	v_add3_u32 v0, v58, v139, 0
	ds_write_b128 v0, v[106:109] offset:128
	s_or_b64 exec, exec, s[48:49]
	s_cmp_lt_i32 s5, -1
	s_waitcnt lgkmcnt(0)
	s_barrier
	s_cbranch_scc1 .LBB0_606
; #define LAS __attribute__((address_space(3)))
; __device__ __forceinline__ unsigned pk2(float a, float b) { f32x2 v = {a, b}; bf16x2_t r = __builtin_convertvector(v, bf16x2_t); return __builtin_bit_cast(unsigned, r); }
; __device__ __forceinline__ void q_prologue(const Params& p, int l, int qrow, int pos, int h, int hf, int lane, bf16x8 (&qf)[6]) {
;     ...
;     const float rs = rsqrtf(ss * (1.f / DQK) + EPS) * 0.14724444602590306f;
; #pragma unroll
;     for (int s = 0; s < 6; ++s) { const float* g = qn + 16 * s + 8 * hf; u32x4 w;
;         w.x = pk2(v[s][0] * rs * g[0], v[s][1] * rs * g[1]); w.y = pk2(v[s][2] * rs * g[2], v[s][3] * rs * g[3]);
;         w.z = pk2(v[s][4] * rs * g[4], v[s][5] * rs * g[5]); w.w = pk2(v[s][6] * rs * g[6], v[s][7] * rs * g[7]);
;         qf[s] = __builtin_bit_cast(bf16x8, w); }
; __device__ __forceinline__ void attn_item(const Params& p, int l, LAS unsigned char* lds, int b, int h, int J) {
;     ...
;     f32x16 o0, o1;
; #pragma unroll
;     for (int q = 0; q < 16; ++q) { o0[q] = 0.f; o1[q] = 0.f; }
;     float mrun = -INFINITY, lsum = 0.f;
; #pragma nounroll
;     for (int j = 0; j < blk_nt; ++j) {
;         LAS unsigned char* cur = lds + (j & 1) * ATT_BUF; LAS unsigned char* nxt = lds + ((j + 1) & 1) * ATT_BUF;
;         const bool more = (j + 1) < blk_nt;
;         if (more) { skn = *(const u32x4*)(gkn + (size_t)(j + 1) * 64 * 512); svt = *(const u32x4*)(gvt + (size_t)(j + 1) * 512 * 64); if (has_kr) skr = *(const u32x4*)(gkr + (size_t)(j + 1) * 64 * 256); }
	v_add_f32_e32 v0, v2, v3
	v_fmamk_f32 v0, v0, 0x3c2aaaab, v210
	v_mul_f32_e32 v2, 0x4b800000, v0
	v_cmp_gt_f32_e32 vcc, s95, v0
	s_movk_i32 s12, 0x70
	s_ashr_i32 s10, s10, 1
	v_cndmask_b32_e32 v0, v0, v2, vcc
	v_rsq_f32_e32 v0, v0
	s_lshl_b32 s5, s5, 2
	s_add_i32 s11, s10, 2
	s_add_i32 s5, s5, 5
	v_mul_f32_e32 v2, 0x45800000, v0
	v_cndmask_b32_e32 v0, v0, v2, vcc
	v_mul_f32_e32 v0, 0x3e16c740, v0
	v_pk_mul_f32 v[2:3], v[0:1], v[128:129] op_sel_hi:[0,1]
	s_waitcnt vmcnt(0)
	v_pk_mul_f32 v[2:3], v[52:53], v[2:3]
	v_pk_mul_f32 v[4:5], v[0:1], v[4:5] op_sel_hi:[0,1]
	v_cvt_pk_bf16_f32 v110, v2, v3
	v_pk_mul_f32 v[2:3], v[0:1], v[126:127] op_sel_hi:[0,1]
	v_pk_mul_f32 v[2:3], v[6:7], v[2:3]
	v_pk_mul_f32 v[4:5], v[54:55], v[4:5]
	v_cvt_pk_bf16_f32 v112, v2, v3
	v_pk_mul_f32 v[2:3], v[0:1], v[118:119] op_sel_hi:[0,1]
	v_pk_mul_f32 v[2:3], v[8:9], v[2:3]
	v_cvt_pk_bf16_f32 v111, v4, v5
	v_cvt_pk_bf16_f32 v113, v2, v3
	v_pk_mul_f32 v[2:3], v[0:1], v[114:115] op_sel_hi:[0,1]
	v_pk_mul_f32 v[2:3], v[48:49], v[2:3]
	v_mov_b32_e32 v4, v1
	v_cvt_pk_bf16_f32 v114, v2, v3
	v_pk_mul_f32 v[2:3], v[0:1], v[116:117] op_sel_hi:[0,1]
	v_pk_mul_f32 v[2:3], v[50:51], v[2:3]
	v_mov_b32_e32 v5, v1
	v_cvt_pk_bf16_f32 v115, v2, v3
	v_pk_mul_f32 v[2:3], v[0:1], v[96:97] op_sel_hi:[0,1]
	v_pk_mul_f32 v[2:3], v[10:11], v[2:3]
	v_mov_b32_e32 v6, v1
	v_cvt_pk_bf16_f32 v116, v2, v3
	v_pk_mul_f32 v[2:3], v[0:1], v[92:93] op_sel_hi:[0,1]
	v_pk_mul_f32 v[2:3], v[12:13], v[2:3]
	v_mov_b32_e32 v7, v1
	v_cvt_pk_bf16_f32 v117, v2, v3
	v_pk_mul_f32 v[2:3], v[0:1], v[90:91] op_sel_hi:[0,1]
	v_pk_mul_f32 v[2:3], v[44:45], v[2:3]
	v_mov_b32_e32 v8, v1
	v_cvt_pk_bf16_f32 v118, v2, v3
	v_pk_mul_f32 v[2:3], v[0:1], v[88:89] op_sel_hi:[0,1]
	v_pk_mul_f32 v[2:3], v[46:47], v[2:3]
	v_mov_b32_e32 v9, v1
	v_cvt_pk_bf16_f32 v119, v2, v3
	v_pk_mul_f32 v[2:3], v[0:1], v[86:87] op_sel_hi:[0,1]
	v_pk_mul_f32 v[2:3], v[14:15], v[2:3]
	v_mov_b32_e32 v14, v1
	v_cvt_pk_bf16_f32 v120, v2, v3
	v_pk_mul_f32 v[2:3], v[0:1], v[84:85] op_sel_hi:[0,1]
	v_pk_mul_f32 v[2:3], v[16:17], v[2:3]
	v_mov_b32_e32 v15, v1
	v_cvt_pk_bf16_f32 v121, v2, v3
	v_pk_mul_f32 v[2:3], v[0:1], v[82:83] op_sel_hi:[0,1]
	v_pk_mul_f32 v[2:3], v[40:41], v[2:3]
	v_mov_b32_e32 v10, v1
	v_cvt_pk_bf16_f32 v122, v2, v3
	v_pk_mul_f32 v[2:3], v[0:1], v[80:81] op_sel_hi:[0,1]
	v_pk_mul_f32 v[2:3], v[42:43], v[2:3]
	v_mov_b32_e32 v11, v1
	v_cvt_pk_bf16_f32 v123, v2, v3
	v_pk_mul_f32 v[2:3], v[0:1], v[78:79] op_sel_hi:[0,1]
	v_pk_mul_f32 v[2:3], v[36:37], v[2:3]
	v_mov_b32_e32 v12, v1
	v_cvt_pk_bf16_f32 v124, v2, v3
	v_pk_mul_f32 v[2:3], v[0:1], v[76:77] op_sel_hi:[0,1]
	v_pk_mul_f32 v[2:3], v[38:39], v[2:3]
	v_mov_b32_e32 v13, v1
	v_cvt_pk_bf16_f32 v125, v2, v3
	v_pk_mul_f32 v[2:3], v[74:75], v[0:1] op_sel_hi:[1,0]
	v_mul_u32_u24_e32 v237, 0x90, v59
	v_pk_mul_f32 v[2:3], v[32:33], v[2:3]
	v_add_u32_e32 v239, v58, v139
	v_cvt_pk_bf16_f32 v126, v2, v3
	v_pk_mul_f32 v[2:3], v[72:73], v[0:1] op_sel_hi:[1,0]
	s_mov_b32 s13, 0
	v_pk_mul_f32 v[2:3], v[34:35], v[2:3]
	v_mov_b32_e32 v250, 0xff800000
	v_cvt_pk_bf16_f32 v127, v2, v3
	v_pk_mul_f32 v[2:3], v[70:71], v[0:1] op_sel_hi:[1,0]
	v_mov_b32_e32 v249, 0
	v_pk_mul_f32 v[2:3], v[18:19], v[2:3]
	s_nop 0
	v_cvt_pk_bf16_f32 v128, v2, v3
	v_pk_mul_f32 v[2:3], v[68:69], v[0:1] op_sel_hi:[1,0]
	s_nop 0
	v_pk_mul_f32 v[2:3], v[20:21], v[2:3]
	s_nop 0
	v_cvt_pk_bf16_f32 v129, v2, v3
	v_pk_mul_f32 v[2:3], v[22:23], v[0:1] op_sel_hi:[1,0]
	s_nop 0
	v_pk_mul_f32 v[2:3], v[28:29], v[2:3]
	s_nop 0
	v_cvt_pk_bf16_f32 v130, v2, v3
	v_pk_mul_f32 v[2:3], v[64:65], v[0:1] op_sel_hi:[1,0]
	s_nop 0
	v_pk_mul_f32 v[2:3], v[30:31], v[2:3]
	s_nop 0
	v_cvt_pk_bf16_f32 v131, v2, v3
	v_pk_mul_f32 v[2:3], v[62:63], v[0:1] op_sel_hi:[1,0]
	s_nop 0
	v_pk_mul_f32 v[2:3], v[24:25], v[2:3]
	s_nop 0
	v_cvt_pk_bf16_f32 v132, v2, v3
	v_pk_mul_f32 v[2:3], v[60:61], v[0:1] op_sel_hi:[1,0]
	v_and_b32_e32 v0, 19, v136
	v_pk_mul_f32 v[2:3], v[2:3], v[26:27]
	s_nop 0
	v_cvt_pk_bf16_f32 v133, v2, v3
	v_lshlrev_b32_e32 v2, 1, v136
	v_lshrrev_b32_e32 v3, 1, v136
	v_and_b32_e32 v2, 8, v2
	v_and_b32_e32 v3, 4, v3
	v_or3_b32 v0, v0, v2, v3
	v_mul_u32_u24_e32 v233, 0xd0, v0
	v_add_u32_e32 v0, s46, v138
	v_lshlrev_b64 v[2:3], 9, v[0:1]
	v_lshl_or_b32 v2, v137, 4, v2
	v_lshl_add_u64 v[240:241], s[38:39], 0, v[2:3]
	v_lshl_add_u64 v[2:3], s[46:47], 0, v[56:57]
	v_lshlrev_b64 v[2:3], 10, v[2:3]
	v_lshl_or_b32 v2, v135, 4, v2
	v_lshl_add_u32 v0, v135, 13, s8
	v_lshl_add_u64 v[242:243], s[42:43], 0, v[2:3]
	v_and_b32_e32 v0, 0xffff0000, v0
	v_lshlrev_b64 v[2:3], 7, v[56:57]
	v_lshl_add_u64 v[2:3], v[0:1], 0, v[2:3]
	v_add_lshl_u32 v0, s46, v134, 1
	v_and_or_b32 v2, v0, s12, v2
	v_lshl_add_u64 v[244:245], s[44:45], 0, v[2:3]
	v_mov_b32_e32 v0, v1
	v_mov_b32_e32 v2, v1
	v_mov_b32_e32 v3, v1
	v_mov_b64_e32 v[32:33], v[14:15]
	v_mov_b64_e32 v[30:31], v[12:13]
	v_mov_b64_e32 v[28:29], v[10:11]
	v_mov_b64_e32 v[26:27], v[8:9]
	v_mov_b64_e32 v[24:25], v[6:7]
	v_mov_b64_e32 v[22:23], v[4:5]
	v_mov_b64_e32 v[20:21], v[2:3]
	v_mov_b64_e32 v[18:19], v[0:1]
	v_mov_b64_e32 v[16:17], v[14:15]
	v_mov_b64_e32 v[14:15], v[12:13]
	v_mov_b64_e32 v[12:13], v[10:11]
	v_mov_b64_e32 v[10:11], v[8:9]
	v_mov_b64_e32 v[8:9], v[6:7]
	v_mov_b64_e32 v[6:7], v[4:5]
	v_mov_b64_e32 v[4:5], v[2:3]
	v_mov_b64_e32 v[2:3], v[0:1]
	s_cmp_eq_u64 s[40:41], 0
	s_cbranch_scc0 .Latt_head
	s_barrier
.Latt_head:
	s_add_i32 s12, s13, 1
	s_cmp_lt_i32 s12, s5
	s_cbranch_scc0 .Latt_nold
	global_load_dwordx4 v[98:101], v[242:243], off
	global_load_dwordx4 v[102:105], v[244:245], off
	s_and_saveexec_b64 s[50:51], s[40:41]
	s_cbranch_execz .Latt_ldx
	global_load_dwordx4 v[106:109], v[240:241], off

; #define LAS __attribute__((address_space(3)))
; __device__ __forceinline__ float shx32(float v, int lane) { return __int_as_float(__builtin_amdgcn_ds_bpermute((lane ^ 32) << 2, __float_as_int(v))); }
; template <bool MASKED>
; __device__ __forceinline__ void attn_step(const bf16x8 (&ka)[2][6], const bf16x8 (&va)[2][4], const bf16x8 (&qf)[6], int nvalid, int lane, f32x16& o0, f32x16& o1, float& mrun, float& lsum) {
;     ...
;     for (int s = 0; s < 6; ++s) { s0 = __builtin_amdgcn_mfma_f32_32x32x16_bf16(ka[0][s], qf[s], s0, 0, 0, 0); s1 = __builtin_amdgcn_mfma_f32_32x32x16_bf16(ka[1][s], qf[s], s1, 0, 0, 0); }
;     if (MASKED) {
; #pragma unroll
;         for (int i = 0; i < 16; ++i) { if (16 * (i >> 3) >= nvalid) s0[i] = -INFINITY; if (32 + 16 * (i >> 3) >= nvalid) s1[i] = -INFINITY; }
;     }
;     float mx = fmaxf(fmaxf(s0[0], s0[1]), s0[2]);
; #pragma unroll
;     for (int i = 3; i < 15; i += 2) mx = fmaxf(fmaxf(mx, s0[i]), s0[i + 1]);
;     mx = fmaxf(mx, s0[15]);
; #pragma unroll
;     for (int i = 0; i < 16; i += 2) mx = fmaxf(fmaxf(mx, s1[i]), s1[i + 1]);
;     if (__builtin_amdgcn_ballot_w64(mx > mrun + 8.0f) != 0ull) {
;         mx = fmaxf(mx, shx32(mx, lane));
;         const float mnew = fmaxf(mrun, mx);
;         const float alpha = __builtin_amdgcn_exp2f(mrun - mnew);
;         mrun = mnew; lsum *= alpha;
; #pragma unroll
;         for (int i = 0; i < 16; ++i) { o0[i] *= alpha; o1[i] *= alpha; }
;     }
; __device__ __forceinline__ void attn_item(const Params& p, int l, LAS unsigned char* lds, int b, int h, int J) {
;     ...
;         if (j < my_nt) {
;             bf16x8 ka[2][6], va[2][4];
; #pragma unroll
;             for (int kb = 0; kb < 2; ++kb)
; #pragma unroll
;                 for (int s = 0; s < 6; ++s) ka[kb][s] = *(const LAS bf16x8*)(cur + rk + kb * 32 * KROW + 32 * s);
; #pragma unroll
;             for (int dvb = 0; dvb < 2; ++dvb)
; #pragma unroll
;                 for (int ks = 0; ks < 4; ++ks) va[dvb][ks] = *(const LAS bf16x8*)(cur + rv + dvb * 32 * VROW + 32 * ks);
;             __builtin_amdgcn_sched_barrier(0);
;             if (j < my_nt - 1) attn_step<false>(ka, va, qf, 64, lane, o0, o1, mrun, lsum); else attn_step<true>(ka, va, qf, 16, lane, o0, o1, mrun, lsum);
;         }
;         if (more) { *(LAS u32x4*)(nxt + wkn) = skn; *(LAS u32x4*)(nxt + wvt) = svt; if (has_kr) *(LAS u32x4*)(nxt + wkr) = skr; }
.Latt_nold:
	s_cmp_ge_i32 s13, s11
	s_cbranch_scc1 .Latt_skip
	s_bitcmp1_b32 s13, 0
	s_cselect_b32 s14, 0x5800, 0
	s_add_i32 s14, s14, 0
	v_add3_u32 v0, s14, v233, v236
	ds_read_b128 v[186:189], v0
	ds_read_b128 v[182:185], v0 offset:32
	ds_read_b128 v[178:181], v0 offset:64
	ds_read_b128 v[174:177], v0 offset:96
	ds_read_b128 v[170:173], v0 offset:128
	ds_read_b128 v[166:169], v0 offset:160
	ds_read_b128 v[50:53], v0 offset:6656
	ds_read_b128 v[206:209], v0 offset:6688
	ds_read_b128 v[202:205], v0 offset:6720
	ds_read_b128 v[198:201], v0 offset:6752
	ds_read_b128 v[194:197], v0 offset:6784
	ds_read_b128 v[190:193], v0 offset:6816
	v_add3_u32 v0, s14, v237, v236
	ds_read_b128 v[158:161], v0 offset:13312
	ds_read_b128 v[150:153], v0 offset:13344
	ds_read_b128 v[146:149], v0 offset:13376
	ds_read_b128 v[138:141], v0 offset:13408
	ds_read_b128 v[162:165], v0 offset:17920
	ds_read_b128 v[154:157], v0 offset:17952
	ds_read_b128 v[142:145], v0 offset:17984
	ds_read_b128 v[134:137], v0 offset:18016
	s_cmp_gt_i32 s13, s10
	v_add_f32_e32 v212, 0x41000000, v250
	s_cbranch_scc1 .Latt_masked
	s_waitcnt lgkmcnt(14)
	v_mfma_f32_32x32x16_bf16 v[66:81], v[186:189], v[110:113], 0
	v_mfma_f32_32x32x16_bf16 v[66:81], v[182:185], v[114:117], v[66:81]
	s_waitcnt lgkmcnt(13)
	v_mfma_f32_32x32x16_bf16 v[50:65], v[50:53], v[110:113], 0
	v_mfma_f32_32x32x16_bf16 v[66:81], v[178:181], v[118:121], v[66:81]
	s_waitcnt lgkmcnt(12)
	v_mfma_f32_32x32x16_bf16 v[50:65], v[206:209], v[114:117], v[50:65]
	v_mfma_f32_32x32x16_bf16 v[66:81], v[174:177], v[122:125], v[66:81]
	s_waitcnt lgkmcnt(11)
	v_mfma_f32_32x32x16_bf16 v[50:65], v[202:205], v[118:121], v[50:65]
	v_mfma_f32_32x32x16_bf16 v[66:81], v[170:173], v[126:129], v[66:81]
	s_waitcnt lgkmcnt(10)
	v_mfma_f32_32x32x16_bf16 v[50:65], v[198:201], v[122:125], v[50:65]
	v_mfma_f32_32x32x16_bf16 v[66:81], v[166:169], v[130:133], v[66:81]
	s_waitcnt lgkmcnt(9)
	v_mfma_f32_32x32x16_bf16 v[50:65], v[194:197], v[126:129], v[50:65]
	s_nop 9
	v_max_f32_e32 v0, v67, v67
	v_max_f32_e32 v34, v66, v66
	v_max_f32_e32 v0, v34, v0
	v_max3_f32 v0, v0, v68, v69
	v_max3_f32 v0, v0, v70, v71
	v_max3_f32 v0, v0, v72, v73
	v_max3_f32 v0, v0, v74, v75
	s_waitcnt lgkmcnt(8)
	v_mfma_f32_32x32x16_bf16 v[50:65], v[190:193], v[130:133], v[50:65]
	v_max3_f32 v0, v0, v76, v77
	v_max3_f32 v0, v0, v78, v79
	v_max3_f32 v0, v0, v80, v81
	s_nop 8
	v_max3_f32 v0, v0, v50, v51
	v_max3_f32 v0, v0, v52, v53
	v_max3_f32 v0, v0, v54, v55
	v_max3_f32 v0, v0, v56, v57
	v_max3_f32 v0, v0, v58, v59
	v_max3_f32 v0, v0, v60, v61
	v_max3_f32 v0, v0, v62, v63
	v_max3_f32 v0, v0, v64, v65
	s_cmp_lt_i32 s12, s5
	s_cbranch_scc0 .Latt_noe_main
	s_bitcmp1_b32 s12, 0
	s_cselect_b32 s14, 0x5800, 0
	v_add_u32_e32 v34, s14, v234
	s_waitcnt vmcnt(1)
	ds_write_b128 v34, v[98:101]
	v_add_u32_e32 v34, s14, v238
	s_waitcnt vmcnt(0)
	ds_write_b128 v34, v[102:105] offset:13312
	s_and_saveexec_b64 s[50:51], s[40:41]
	v_add_u32_e32 v34, s14, v239
	ds_write_b128 v34, v[106:109] offset:128
	s_or_b64 exec, exec, s[50:51]
.Latt_noe_main:
	s_waitcnt lgkmcnt(0)
	s_barrier
	v_cmp_gt_f32_e32 vcc, v0, v212
	s_cbranch_vccz .Latt_norescale
	ds_bpermute_b32 v34, v235, v0
	s_waitcnt lgkmcnt(0)
	v_max3_f32 v213, v250, v0, v34
	v_sub_f32_e32 v0, v250, v213
	v_exp_f32_e32 v0, v0
	s_nop 0
	v_mul_f32_e32 v249, v249, v0
	v_pk_mul_f32 v[32:33], v[32:33], v[0:1] op_sel_hi:[1,0]
	v_pk_mul_f32 v[30:31], v[30:31], v[0:1] op_sel_hi:[1,0]
	v_pk_mul_f32 v[28:29], v[28:29], v[0:1] op_sel_hi:[1,0]
	v_pk_mul_f32 v[26:27], v[26:27], v[0:1] op_sel_hi:[1,0]
	v_pk_mul_f32 v[24:25], v[24:25], v[0:1] op_sel_hi:[1,0]
	v_pk_mul_f32 v[22:23], v[22:23], v[0:1] op_sel_hi:[1,0]
	v_pk_mul_f32 v[20:21], v[20:21], v[0:1] op_sel_hi:[1,0]
	v_pk_mul_f32 v[18:19], v[18:19], v[0:1] op_sel_hi:[1,0]
	v_pk_mul_f32 v[16:17], v[16:17], v[0:1] op_sel_hi:[1,0]
	v_pk_mul_f32 v[14:15], v[14:15], v[0:1] op_sel_hi:[1,0]
	v_pk_mul_f32 v[12:13], v[12:13], v[0:1] op_sel_hi:[1,0]
	v_pk_mul_f32 v[10:11], v[10:11], v[0:1] op_sel_hi:[1,0]
	v_pk_mul_f32 v[8:9], v[8:9], v[0:1] op_sel_hi:[1,0]
	v_pk_mul_f32 v[6:7], v[6:7], v[0:1] op_sel_hi:[1,0]
	v_pk_mul_f32 v[4:5], v[4:5], v[0:1] op_sel_hi:[1,0]
	v_pk_mul_f32 v[2:3], v[2:3], v[0:1] op_sel_hi:[1,0]
	v_mov_b32_e32 v250, v213
	v_mov_b32_e32 v0, v213
	s_branch .Latt_softmax

; template <bool MASKED>
; __device__ __forceinline__ void attn_step(const bf16x8 (&ka)[2][6], const bf16x8 (&va)[2][4], const bf16x8 (&qf)[6], int nvalid, int lane, f32x16& o0, f32x16& o1, float& mrun, float& lsum) {
;     ...
;     for (int s = 0; s < 6; ++s) { s0 = __builtin_amdgcn_mfma_f32_32x32x16_bf16(ka[0][s], qf[s], s0, 0, 0, 0); s1 = __builtin_amdgcn_mfma_f32_32x32x16_bf16(ka[1][s], qf[s], s1, 0, 0, 0); }
;     if (MASKED) {
; #pragma unroll
;         for (int i = 0; i < 16; ++i) { if (16 * (i >> 3) >= nvalid) s0[i] = -INFINITY; if (32 + 16 * (i >> 3) >= nvalid) s1[i] = -INFINITY; }
;     }
;     float mx = fmaxf(fmaxf(s0[0], s0[1]), s0[2]);
; #pragma unroll
;     for (int i = 3; i < 15; i += 2) mx = fmaxf(fmaxf(mx, s0[i]), s0[i + 1]);
;     mx = fmaxf(mx, s0[15]);
; #pragma unroll
;     for (int i = 0; i < 16; i += 2) mx = fmaxf(fmaxf(mx, s1[i]), s1[i + 1]);
;     if (__builtin_amdgcn_ballot_w64(mx > mrun + 8.0f) != 0ull) {
;         mx = fmaxf(mx, shx32(mx, lane));
;     ...
;     {
;         const f32x2 m2 = {mrun, mrun}; f32x2 acc2 = {0.f, 0.f};
; #pragma unroll
;         for (int i = 0; i < 16; i += 2) {
;             f32x2 a = (f32x2){s0[i], s0[i + 1]} - m2, c = (f32x2){s1[i], s1[i + 1]} - m2;
;             a.x = __builtin_amdgcn_exp2f(a.x); a.y = __builtin_amdgcn_exp2f(a.y); c.x = __builtin_amdgcn_exp2f(c.x); c.y = __builtin_amdgcn_exp2f(c.y);
;             acc2 = acc2 + a; acc2 = acc2 + c;
;             s0[i] = a.x; s0[i + 1] = a.y; s1[i] = c.x; s1[i + 1] = c.y;
;         }
;         lsum += acc2.x + acc2.y;
;     }
;     bf16x8 pf[4];
;     { u32x4 w;
;       w.x = pk2(s0[0], s0[1]); w.y = pk2(s0[2], s0[3]); w.z = pk2(s0[4], s0[5]); w.w = pk2(s0[6], s0[7]); pf[0] = __builtin_bit_cast(bf16x8, w);
;       w.x = pk2(s0[8], s0[9]); w.y = pk2(s0[10], s0[11]); w.z = pk2(s0[12], s0[13]); w.w = pk2(s0[14], s0[15]); pf[1] = __builtin_bit_cast(bf16x8, w);
;       w.x = pk2(s1[0], s1[1]); w.y = pk2(s1[2], s1[3]); w.z = pk2(s1[4], s1[5]); w.w = pk2(s1[6], s1[7]); pf[2] = __builtin_bit_cast(bf16x8, w);
;       w.x = pk2(s1[8], s1[9]); w.y = pk2(s1[10], s1[11]); w.z = pk2(s1[12], s1[13]); w.w = pk2(s1[14], s1[15]); pf[3] = __builtin_bit_cast(bf16x8, w); }
; #pragma unroll
;     for (int ks = 0; ks < 4; ++ks) { o0 = __builtin_amdgcn_mfma_f32_32x32x16_bf16(va[0][ks], pf[ks], o0, 0, 0, 0); o1 = __builtin_amdgcn_mfma_f32_32x32x16_bf16(va[1][ks], pf[ks], o1, 0, 0, 0); }
.Latt_softmax:
	v_pk_add_f32 v[66:67], v[66:67], v[0:1] op_sel_hi:[1,0] neg_lo:[0,1] neg_hi:[0,1]
	v_pk_add_f32 v[50:51], v[50:51], v[0:1] op_sel_hi:[1,0] neg_lo:[0,1] neg_hi:[0,1]
	v_exp_f32_e32 v66, v66
	v_exp_f32_e32 v67, v67
	v_exp_f32_e32 v192, v50
	v_exp_f32_e32 v193, v51
	v_pk_add_f32 v[68:69], v[68:69], v[0:1] op_sel_hi:[1,0] neg_lo:[0,1] neg_hi:[0,1]
	v_pk_add_f32 v[52:53], v[52:53], v[0:1] op_sel_hi:[1,0] neg_lo:[0,1] neg_hi:[0,1]
	v_exp_f32_e32 v68, v68
	v_exp_f32_e32 v69, v69
	v_exp_f32_e32 v194, v52
	v_exp_f32_e32 v195, v53
	v_pk_add_f32 v[52:53], v[70:71], v[0:1] op_sel_hi:[1,0] neg_lo:[0,1] neg_hi:[0,1]
	v_pk_add_f32 v[50:51], v[66:67], 0 op_sel_hi:[1,0]
	v_pk_add_f32 v[54:55], v[54:55], v[0:1] op_sel_hi:[1,0] neg_lo:[0,1] neg_hi:[0,1]
	v_exp_f32_e32 v52, v52
	v_exp_f32_e32 v53, v53
	v_pk_add_f32 v[50:51], v[192:193], v[50:51]
	v_exp_f32_e32 v54, v54
	v_exp_f32_e32 v55, v55
	v_pk_add_f32 v[50:51], v[68:69], v[50:51]
	v_pk_add_f32 v[74:75], v[74:75], v[0:1] op_sel_hi:[1,0] neg_lo:[0,1] neg_hi:[0,1]
	v_pk_add_f32 v[50:51], v[194:195], v[50:51]
	v_exp_f32_e32 v74, v74
	v_pk_add_f32 v[50:51], v[52:53], v[50:51]
	v_cvt_pk_bf16_f32 v52, v52, v53
	v_pk_add_f32 v[70:71], v[54:55], v[50:51]
	v_pk_add_f32 v[50:51], v[72:73], v[0:1] op_sel_hi:[1,0] neg_lo:[0,1] neg_hi:[0,1]
	v_exp_f32_e32 v75, v75
	v_exp_f32_e32 v72, v50
	v_exp_f32_e32 v73, v51
	v_cvt_pk_bf16_f32 v50, v66, v67
	v_cvt_pk_bf16_f32 v51, v68, v69
	v_pk_add_f32 v[66:67], v[76:77], v[0:1] op_sel_hi:[1,0] neg_lo:[0,1] neg_hi:[0,1]
	v_cvt_pk_bf16_f32 v53, v72, v73
	v_pk_add_f32 v[68:69], v[78:79], v[0:1] op_sel_hi:[1,0] neg_lo:[0,1] neg_hi:[0,1]
	v_exp_f32_e32 v66, v66
	s_waitcnt lgkmcnt(7)
	v_mfma_f32_32x32x16_bf16 v[18:33], v[158:161], v[50:53], v[18:33]
	v_exp_f32_e32 v67, v67
	v_exp_f32_e32 v68, v68
	v_exp_f32_e32 v69, v69
	v_pk_add_f32 v[56:57], v[56:57], v[0:1] op_sel_hi:[1,0] neg_lo:[0,1] neg_hi:[0,1]
	v_pk_add_f32 v[58:59], v[58:59], v[0:1] op_sel_hi:[1,0] neg_lo:[0,1] neg_hi:[0,1]
	v_exp_f32_e32 v56, v56
	v_exp_f32_e32 v57, v57
	s_waitcnt lgkmcnt(3)
	v_mfma_f32_32x32x16_bf16 v[2:17], v[162:165], v[50:53], v[2:17]
	v_add_f32_e64 v50, v80, -v0
	v_add_f32_e64 v51, v81, -v0
	v_cvt_pk_bf16_f32 v52, v68, v69
	v_exp_f32_e32 v76, v50
	v_exp_f32_e32 v77, v51
	v_cvt_pk_bf16_f32 v50, v74, v75
	v_cvt_pk_bf16_f32 v51, v66, v67
	v_exp_f32_e32 v58, v58
	v_cvt_pk_bf16_f32 v53, v76, v77
	v_exp_f32_e32 v59, v59
	v_pk_add_f32 v[70:71], v[72:73], v[70:71]
	v_mfma_f32_32x32x16_bf16 v[18:33], v[150:153], v[50:53], v[18:33]
	s_waitcnt lgkmcnt(2)
	v_mfma_f32_32x32x16_bf16 v[2:17], v[154:157], v[50:53], v[2:17]
	v_add_f32_e64 v50, v56, v70
	v_add_f32_e64 v51, v57, v71
	v_cvt_pk_bf16_f32 v52, v54, v55
	v_add_f32_e64 v50, v74, v50
	v_add_f32_e64 v51, v75, v51
	v_cvt_pk_bf16_f32 v53, v56, v57
	v_pk_add_f32 v[70:71], v[58:59], v[50:51]
	v_cvt_pk_bf16_f32 v50, v192, v193
	v_cvt_pk_bf16_f32 v51, v194, v195
	v_pk_add_f32 v[54:55], v[60:61], v[0:1] op_sel_hi:[1,0] neg_lo:[0,1] neg_hi:[0,1]
	v_pk_add_f32 v[60:61], v[62:63], v[0:1] op_sel_hi:[1,0] neg_lo:[0,1] neg_hi:[0,1]
	v_mfma_f32_32x32x16_bf16 v[18:33], v[146:149], v[50:53], v[18:33]
	v_exp_f32_e32 v54, v54
	v_exp_f32_e32 v55, v55
	v_exp_f32_e32 v60, v60
	v_exp_f32_e32 v61, v61
	v_pk_add_f32 v[56:57], v[66:67], v[70:71]
	s_waitcnt lgkmcnt(1)
	v_mfma_f32_32x32x16_bf16 v[2:17], v[142:145], v[50:53], v[2:17]
	v_add_f32_e64 v50, v64, -v0
	v_add_f32_e64 v51, v65, -v0
	v_cvt_pk_bf16_f32 v52, v60, v61
	v_exp_f32_e32 v62, v50
	v_exp_f32_e32 v63, v51
	v_cvt_pk_bf16_f32 v50, v58, v59
	v_cvt_pk_bf16_f32 v51, v54, v55
	v_pk_add_f32 v[54:55], v[54:55], v[56:57]
	v_cvt_pk_bf16_f32 v53, v62, v63
	v_pk_add_f32 v[54:55], v[68:69], v[54:55]
	s_nop 0
	v_mfma_f32_32x32x16_bf16 v[18:33], v[138:141], v[50:53], v[18:33]
	v_add_f32_e64 v54, v60, v54
	v_add_f32_e64 v55, v61, v55
	v_add_f32_e64 v54, v76, v54
	v_add_f32_e64 v55, v77, v55
	v_add_f32_e64 v54, v62, v54
	v_add_f32_e64 v55, v63, v55
	v_add_f32_e32 v0, v54, v55
	s_waitcnt lgkmcnt(0)
	v_mfma_f32_32x32x16_bf16 v[2:17], v[134:137], v[50:53], v[2:17]
	v_add_f32_e32 v249, v249, v0
	v_mov_b64_e32 v[200:201], v[216:217]
	s_branch .Latt_end
.Latt_masked:
	s_cmp_lt_i32 s12, s5
	s_cbranch_scc0 .Latt_noe_mask
	s_bitcmp1_b32 s12, 0
	s_cselect_b32 s14, 0x5800, 0
	v_add_u32_e32 v0, s14, v234
	s_waitcnt vmcnt(1)
	ds_write_b128 v0, v[98:101]
	v_add_u32_e32 v0, s14, v238
	s_waitcnt vmcnt(0)
	ds_write_b128 v0, v[102:105] offset:13312
	s_and_saveexec_b64 s[50:51], s[40:41]
	v_add_u32_e32 v0, s14, v239
	ds_write_b128 v0, v[106:109] offset:128
	s_or_b64 exec, exec, s[50:51]
.Latt_noe_mask:
	s_waitcnt lgkmcnt(0)
	s_barrier
	v_mov_b64_e32 v[200:201], v[216:217]
	v_mfma_f32_32x32x16_bf16 v[34:49], v[186:189], v[110:113], 0
	v_mfma_f32_32x32x16_bf16 v[34:49], v[182:185], v[114:117], v[34:49]
	v_mfma_f32_32x32x16_bf16 v[34:49], v[178:181], v[118:121], v[34:49]
	v_mfma_f32_32x32x16_bf16 v[34:49], v[174:177], v[122:125], v[34:49]
	v_mfma_f32_32x32x16_bf16 v[34:49], v[170:173], v[126:129], v[34:49]
	v_mfma_f32_32x32x16_bf16 v[34:49], v[166:169], v[130:133], v[34:49]
	s_nop 11
	v_max3_f32 v0, v34, v35, v36
	v_max3_f32 v0, v0, v37, v38
	v_max3_f32 v0, v0, v39, v40
	v_max3_f32 v0, v0, v41, s59
	v_cmp_gt_f32_e32 vcc, v0, v212
	s_cbranch_vccz .LBB0_628
	ds_bpermute_b32 v42, v235, v0
	s_waitcnt lgkmcnt(0)
	v_max3_f32 v0, v250, v0, v42
	v_sub_f32_e32 v42, v250, v0
	v_exp_f32_e32 v42, v42
	v_mov_b32_e32 v250, v0
	v_mul_f32_e32 v249, v249, v42
	v_pk_mul_f32 v[32:33], v[32:33], v[42:43] op_sel_hi:[1,0]
	v_pk_mul_f32 v[30:31], v[30:31], v[42:43] op_sel_hi:[1,0]
	v_pk_mul_f32 v[28:29], v[28:29], v[42:43] op_sel_hi:[1,0]
	v_pk_mul_f32 v[26:27], v[26:27], v[42:43] op_sel_hi:[1,0]
	v_pk_mul_f32 v[24:25], v[24:25], v[42:43] op_sel_hi:[1,0]
	v_pk_mul_f32 v[22:23], v[22:23], v[42:43] op_sel_hi:[1,0]
	v_pk_mul_f32 v[20:21], v[20:21], v[42:43] op_sel_hi:[1,0]
	v_pk_mul_f32 v[18:19], v[18:19], v[42:43] op_sel_hi:[1,0]
	v_pk_mul_f32 v[16:17], v[16:17], v[42:43] op_sel_hi:[1,0]
	v_pk_mul_f32 v[14:15], v[14:15], v[42:43] op_sel_hi:[1,0]
	v_pk_mul_f32 v[12:13], v[12:13], v[42:43] op_sel_hi:[1,0]
	v_pk_mul_f32 v[10:11], v[10:11], v[42:43] op_sel_hi:[1,0]
	v_pk_mul_f32 v[8:9], v[8:9], v[42:43] op_sel_hi:[1,0]
	v_pk_mul_f32 v[6:7], v[6:7], v[42:43] op_sel_hi:[1,0]
	v_pk_mul_f32 v[4:5], v[4:5], v[42:43] op_sel_hi:[1,0]
	v_pk_mul_f32 v[2:3], v[2:3], v[42:43] op_sel_hi:[1,0]
	s_branch .LBB0_629

; __device__ __forceinline__ unsigned pk2(float a, float b) { f32x2 v = {a, b}; bf16x2_t r = __builtin_convertvector(v, bf16x2_t); return __builtin_bit_cast(unsigned, r); }
; template <bool MASKED>
; __device__ __forceinline__ void attn_step(const bf16x8 (&ka)[2][6], const bf16x8 (&va)[2][4], const bf16x8 (&qf)[6], int nvalid, int lane, f32x16& o0, f32x16& o1, float& mrun, float& lsum) {
;     ...
;     {
;         const f32x2 m2 = {mrun, mrun}; f32x2 acc2 = {0.f, 0.f};
; #pragma unroll
;         for (int i = 0; i < 16; i += 2) {
;             f32x2 a = (f32x2){s0[i], s0[i + 1]} - m2, c = (f32x2){s1[i], s1[i + 1]} - m2;
;             a.x = __builtin_amdgcn_exp2f(a.x); a.y = __builtin_amdgcn_exp2f(a.y); c.x = __builtin_amdgcn_exp2f(c.x); c.y = __builtin_amdgcn_exp2f(c.y);
;             acc2 = acc2 + a; acc2 = acc2 + c;
;             s0[i] = a.x; s0[i + 1] = a.y; s1[i] = c.x; s1[i + 1] = c.y;
;         }
;         lsum += acc2.x + acc2.y;
;     }
;     bf16x8 pf[4];
;     { u32x4 w;
;       w.x = pk2(s0[0], s0[1]); w.y = pk2(s0[2], s0[3]); w.z = pk2(s0[4], s0[5]); w.w = pk2(s0[6], s0[7]); pf[0] = __builtin_bit_cast(bf16x8, w);
;       w.x = pk2(s0[8], s0[9]); w.y = pk2(s0[10], s0[11]); w.z = pk2(s0[12], s0[13]); w.w = pk2(s0[14], s0[15]); pf[1] = __builtin_bit_cast(bf16x8, w);
;       w.x = pk2(s1[0], s1[1]); w.y = pk2(s1[2], s1[3]); w.z = pk2(s1[4], s1[5]); w.w = pk2(s1[6], s1[7]); pf[2] = __builtin_bit_cast(bf16x8, w);
;       w.x = pk2(s1[8], s1[9]); w.y = pk2(s1[10], s1[11]); w.z = pk2(s1[12], s1[13]); w.w = pk2(s1[14], s1[15]); pf[3] = __builtin_bit_cast(bf16x8, w); }
; #pragma unroll
;     for (int ks = 0; ks < 4; ++ks) { o0 = __builtin_amdgcn_mfma_f32_32x32x16_bf16(va[0][ks], pf[ks], o0, 0, 0, 0); o1 = __builtin_amdgcn_mfma_f32_32x32x16_bf16(va[1][ks], pf[ks], o1, 0, 0, 0); }
.LBB0_629:
	v_pk_add_f32 v[34:35], v[34:35], v[0:1] op_sel_hi:[1,0] neg_lo:[0,1] neg_hi:[0,1]
	v_mov_b32_e32 v213, v250
	v_exp_f32_e32 v42, v34
	v_exp_f32_e32 v43, v35
	v_pk_add_f32 v[34:35], v[36:37], v[0:1] op_sel_hi:[1,0] neg_lo:[0,1] neg_hi:[0,1]
	s_nop 0
	v_exp_f32_e32 v44, v34
	v_exp_f32_e32 v45, v35
	v_pk_add_f32 v[34:35], v[38:39], v[0:1] op_sel_hi:[1,0] neg_lo:[0,1] neg_hi:[0,1]
	s_nop 0
	v_exp_f32_e32 v38, v34
	v_exp_f32_e32 v39, v35
	v_pk_add_f32 v[34:35], v[40:41], v[0:1] op_sel_hi:[1,0] neg_lo:[0,1] neg_hi:[0,1]
	v_sub_f32_e32 v0, 0xff800000, v0
	v_exp_f32_e32 v40, v34
	v_exp_f32_e32 v41, v35
	v_cvt_pk_bf16_f32 v34, v42, v43
	v_cvt_pk_bf16_f32 v35, v44, v45
	v_cvt_pk_bf16_f32 v36, v38, v39
	v_cvt_pk_bf16_f32 v37, v40, v41
	v_exp_f32_e32 v0, v0
	s_waitcnt lgkmcnt(7)
	v_mfma_f32_32x32x16_bf16 v[18:33], v[158:161], v[34:37], v[18:33]
	v_cvt_pk_bf16_f32 v50, v0, v0
	v_mov_b32_e32 v51, v50
	v_mov_b32_e32 v52, v50
	v_mov_b32_e32 v53, v50
	s_waitcnt lgkmcnt(3)
	v_mfma_f32_32x32x16_bf16 v[2:17], v[162:165], v[34:37], v[2:17]
	v_add_f32_e64 v34, v42, 0
	v_add_f32_e64 v35, v43, 0
	v_add_f32_e64 v34, v0, v34
	v_add_f32_e64 v35, v0, v35
	v_add_f32_e64 v34, v44, v34
	v_add_f32_e64 v35, v45, v35
	v_pk_add_f32 v[34:35], v[0:1], v[34:35] op_sel_hi:[0,1]
	v_pk_add_f32 v[34:35], v[38:39], v[34:35]
	v_mfma_f32_32x32x16_bf16 v[18:33], v[150:153], v[50:53], v[18:33]
	v_add_f32_e64 v34, v0, v34
	v_add_f32_e64 v35, v0, v35
	v_add_f32_e64 v34, v40, v34
	v_add_f32_e64 v35, v41, v35
	v_add_f32_e64 v34, v0, v34
	v_add_f32_e64 v35, v0, v35
	v_pk_add_f32 v[34:35], v[0:1], v[34:35] op_sel_hi:[0,1]
	v_pk_add_f32 v[34:35], v[0:1], v[34:35] op_sel_hi:[0,1]
	v_pk_add_f32 v[34:35], v[0:1], v[34:35] op_sel_hi:[0,1]
	s_waitcnt lgkmcnt(2)
	v_mfma_f32_32x32x16_bf16 v[2:17], v[154:157], v[50:53], v[2:17]
	v_add_f32_e64 v34, v0, v34
	v_add_f32_e64 v35, v0, v35
	v_add_f32_e64 v34, v0, v34
	v_add_f32_e64 v35, v0, v35
	v_add_f32_e64 v34, v0, v34
	v_add_f32_e64 v35, v0, v35
	v_pk_add_f32 v[34:35], v[0:1], v[34:35] op_sel_hi:[0,1]
	v_pk_add_f32 v[34:35], v[0:1], v[34:35] op_sel_hi:[0,1]
	v_add_f32_e32 v0, v34, v35
	v_add_f32_e32 v249, v249, v0
	v_mfma_f32_32x32x16_bf16 v[18:33], v[146:149], v[50:53], v[18:33]
	s_waitcnt lgkmcnt(1)
	v_mfma_f32_32x32x16_bf16 v[2:17], v[142:145], v[50:53], v[2:17]
	v_mfma_f32_32x32x16_bf16 v[18:33], v[138:141], v[50:53], v[18:33]
	s_waitcnt lgkmcnt(0)
	v_mfma_f32_32x32x16_bf16 v[2:17], v[134:137], v[50:53], v[2:17]
	s_branch .Latt_end

; #define LAS __attribute__((address_space(3)))
; __device__ __forceinline__ void attn_item(const Params& p, int l, LAS unsigned char* lds, int b, int h, int J) {
;     ...
;         if (j < my_nt) {
;     ...
;         if (more) { *(LAS u32x4*)(nxt + wkn) = skn; *(LAS u32x4*)(nxt + wvt) = svt; if (has_kr) *(LAS u32x4*)(nxt + wkr) = skr; }
;         __syncthreads();
.Latt_noe_skip:
	s_waitcnt lgkmcnt(0)
	s_barrier

; #define LAS __attribute__((address_space(3)))
; __device__ __forceinline__ float shx32(float v, int lane) { return __int_as_float(__builtin_amdgcn_ds_bpermute((lane ^ 32) << 2, __float_as_int(v))); }
; __device__ __forceinline__ void attn_item(const Params& p, int l, LAS unsigned char* lds, int b, int h, int J) {
;     ...
;     for (int j = 0; j < blk_nt; ++j) {
;         LAS unsigned char* cur = lds + (j & 1) * ATT_BUF; LAS unsigned char* nxt = lds + ((j + 1) & 1) * ATT_BUF;
;         const bool more = (j + 1) < blk_nt;
;         if (more) { skn = *(const u32x4*)(gkn + (size_t)(j + 1) * 64 * 512); svt = *(const u32x4*)(gvt + (size_t)(j + 1) * 512 * 64); if (has_kr) skr = *(const u32x4*)(gkr + (size_t)(j + 1) * 64 * 256); }
;         if (j < my_nt) {
;             bf16x8 ka[2][6], va[2][4];
; #pragma unroll
;             for (int kb = 0; kb < 2; ++kb)
; #pragma unroll
;                 for (int s = 0; s < 6; ++s) ka[kb][s] = *(const LAS bf16x8*)(cur + rk + kb * 32 * KROW + 32 * s);
; #pragma unroll
;             for (int dvb = 0; dvb < 2; ++dvb)
; #pragma unroll
;                 for (int ks = 0; ks < 4; ++ks) va[dvb][ks] = *(const LAS bf16x8*)(cur + rv + dvb * 32 * VROW + 32 * ks);
;             __builtin_amdgcn_sched_barrier(0);
;             if (j < my_nt - 1) attn_step<false>(ka, va, qf, 64, lane, o0, o1, mrun, lsum); else attn_step<true>(ka, va, qf, 16, lane, o0, o1, mrun, lsum);
;         }
;         if (more) { *(LAS u32x4*)(nxt + wkn) = skn; *(LAS u32x4*)(nxt + wvt) = svt; if (has_kr) *(LAS u32x4*)(nxt + wkr) = skr; }
;         __syncthreads();
;     }
;     lsum += shx32(lsum, lane);
.Latt_exit:
	s_cmp_eq_u64 s[40:41], 0
	s_cbranch_scc1 .LBB0_607
	s_barrier
	s_branch .LBB0_607
